# D3 state wave: dropped the lgkmcnt(0) before the hand-off flag write (LDS issue order keeps the flag behind the v_new pieces; compiler's counted waits cover the kd fragments)
# speedup vs baseline: 1.0009x; 1.0009x over previous
; #define LAS __attribute__((address_space(3)))
; #define MFMA32(a, b, c) __builtin_amdgcn_mfma_f32_32x32x16_bf16((a), (b), (c), 0, 0, 0)
; DI float bflo(unsigned u) { return __uint_as_float(u << 16); }
; DI float bfhi(unsigned u) { return __uint_as_float(u & 0xffff0000u); }
; DI void d3_block(const Params& P, int bh, int vs, LAS unsigned char* lds, int wave, int lane, int tid) {
;     ...
;         for (int n = 0; n < 128; ++n) {
;             const LAS unsigned char* sb = lds + (n & 1) * D3_SLOT;
;             const LAS bf16x8* fNW = (const LAS bf16x8*)sb + lane; const LAS bf16x8* fKD = (const LAS bf16x8*)(sb + 40960) + lane;
;             const LAS u32x4* fU = (const LAS u32x4*)(sb + 57344) + lane * 2;
;             const float gl_next = GL[(n + 1) & 127];
;             bf16x8 fw[16];
; #pragma unroll
;             for (int q = 0; q < 16; ++q) fw[q] = fNW[q * 64];
;             f32x16 vt[2];
; #pragma unroll
;             for (int t = 0; t < 2; ++t) { const u32x4 a = fU[t * 128], b2 = fU[t * 128 + 1];
;                 vt[t][0] = bflo(a.x); vt[t][1] = bfhi(a.x); vt[t][2] = bflo(a.y); vt[t][3] = bfhi(a.y); vt[t][4] = bflo(a.z); vt[t][5] = bfhi(a.z); vt[t][6] = bflo(a.w); vt[t][7] = bfhi(a.w);
;                 vt[t][8] = bflo(b2.x); vt[t][9] = bfhi(b2.x); vt[t][10] = bflo(b2.y); vt[t][11] = bfhi(b2.y); vt[t][12] = bflo(b2.z); vt[t][13] = bfhi(b2.z); vt[t][14] = bflo(b2.w); vt[t][15] = bfhi(b2.w); }
;             __builtin_amdgcn_sched_barrier(0);
; #pragma unroll
;             for (int G = 0; G < 8; ++G) {
;                 vt[0] = MFMA32(fw[G], Sb[G], vt[0]); vt[1] = MFMA32(fw[8 + G], Sb[G], vt[1]);
;                 if (G < 4) {
; #pragma unroll
;                     for (int i = 0; i < 16; ++i) S[G][i] *= gl; } }
;             __builtin_amdgcn_sched_barrier(0);
;             bf16x8 fk[16];
; #pragma unroll
;             for (int q = 0; q < 16; ++q) fk[q] = fKD[q * 64];
;             __builtin_amdgcn_sched_barrier(0);
;             bf16x8 Vb[4];
;             Vb[0] = pack8(vt[0], 0); Vb[1] = pack8(vt[0], 1); Vb[2] = pack8(vt[1], 0); Vb[3] = pack8(vt[1], 1);
; #pragma unroll
;             for (int G = 0; G < 4; ++G) exVb[G * 64] = Vb[G];
;             asm volatile("s_waitcnt lgkmcnt(0)" ::: "memory");
;             if (lane == 0) *vflag = (unsigned)(n + 1);
.LBB0_369:
	s_bitcmp1_b32 s8, 0
	s_cselect_b32 s4, 0xf000, 0
	s_add_i32 s8, s8, 1
	s_and_b32 s5, s8, 0x7f
	s_lshl_b32 s5, s5, 2
	v_mov_b32_e32 v64, s5
	global_load_dword v170, v64, s[0:1]
	s_add_i32 s4, s4, 0
	v_lshl_add_u32 v64, v240, 4, s4
	ds_read_b128 v[130:133], v64
	ds_read_b128 v[134:137], v64 offset:1024
	ds_read_b128 v[138:141], v64 offset:2048
	ds_read_b128 v[142:145], v64 offset:3072
	ds_read_b128 v[146:149], v64 offset:4096
	ds_read_b128 v[150:153], v64 offset:5120
	ds_read_b128 v[154:157], v64 offset:6144
	ds_read_b128 v[158:161], v64 offset:7168
	ds_read_b128 v[162:165], v64 offset:8192
	ds_read_b128 v[172:175], v64 offset:9216
	ds_read_b128 v[176:179], v64 offset:10240
	ds_read_b128 v[184:187], v64 offset:11264
	v_add_u32_e32 v171, s4, v168
	ds_read_b128 v[68:71], v171 offset:57344
	ds_read_b128 v[196:199], v64 offset:12288
	ds_read_b128 v[200:203], v64 offset:13312
	ds_read_b128 v[204:207], v64 offset:14336
	ds_read_b128 v[208:211], v64 offset:15360
	ds_read_b128 v[76:79], v171 offset:57360
	ds_read_b128 v[84:87], v171 offset:59392
	ds_read_b128 v[92:95], v171 offset:59408
	s_waitcnt lgkmcnt(0)
	v_lshlrev_b32_e32 v64, 16, v68
	v_and_b32_e32 v65, 0xffff0000, v68
	v_lshlrev_b32_e32 v66, 16, v69
	v_and_b32_e32 v67, 0xffff0000, v69
	v_lshlrev_b32_e32 v68, 16, v70
	v_and_b32_e32 v69, 0xffff0000, v70
	v_lshlrev_b32_e32 v70, 16, v71
	v_and_b32_e32 v71, 0xffff0000, v71
	v_lshlrev_b32_e32 v72, 16, v76
	v_and_b32_e32 v73, 0xffff0000, v76
	v_lshlrev_b32_e32 v74, 16, v77
	v_and_b32_e32 v75, 0xffff0000, v77
	v_lshlrev_b32_e32 v76, 16, v78
	v_and_b32_e32 v77, 0xffff0000, v78
	v_lshlrev_b32_e32 v78, 16, v79
	v_and_b32_e32 v79, 0xffff0000, v79
	v_lshlrev_b32_e32 v80, 16, v84
	v_and_b32_e32 v81, 0xffff0000, v84
	v_lshlrev_b32_e32 v82, 16, v85
	v_and_b32_e32 v83, 0xffff0000, v85
	v_lshlrev_b32_e32 v84, 16, v86
	v_and_b32_e32 v85, 0xffff0000, v86
	v_lshlrev_b32_e32 v86, 16, v87
	v_and_b32_e32 v87, 0xffff0000, v87
	v_lshlrev_b32_e32 v88, 16, v92
	v_and_b32_e32 v89, 0xffff0000, v92
	v_lshlrev_b32_e32 v90, 16, v93
	v_and_b32_e32 v91, 0xffff0000, v93
	v_lshlrev_b32_e32 v92, 16, v94
	v_and_b32_e32 v93, 0xffff0000, v94
	v_lshlrev_b32_e32 v94, 16, v95
	v_and_b32_e32 v95, 0xffff0000, v95
	v_mfma_f32_32x32x16_bf16 v[64:79], v[130:133], v[98:101], v[64:79]
	v_mul_f32_e32 v0, v96, v0
	v_mul_f32_e32 v1, v96, v1
	v_mul_f32_e32 v2, v96, v2
	v_mul_f32_e32 v3, v96, v3
	v_mfma_f32_32x32x16_bf16 v[80:95], v[162:165], v[98:101], v[80:95]
	v_mul_f32_e32 v4, v96, v4
	v_mul_f32_e32 v5, v96, v5
	v_mul_f32_e32 v6, v96, v6
	v_mul_f32_e32 v7, v96, v7
	v_mfma_f32_32x32x16_bf16 v[64:79], v[134:137], v[102:105], v[64:79]
	v_mul_f32_e32 v8, v96, v8
	v_mul_f32_e32 v9, v96, v9
	v_mul_f32_e32 v10, v96, v10
	v_mul_f32_e32 v11, v96, v11
	v_mfma_f32_32x32x16_bf16 v[80:95], v[172:175], v[102:105], v[80:95]
	v_mul_f32_e32 v12, v96, v12
	v_mul_f32_e32 v13, v96, v13
	v_mul_f32_e32 v14, v96, v14
	v_mul_f32_e32 v15, v96, v15
	v_mfma_f32_32x32x16_bf16 v[64:79], v[138:141], v[106:109], v[64:79]
	v_mul_f32_e32 v16, v96, v16
	v_mul_f32_e32 v17, v96, v17
	v_mul_f32_e32 v18, v96, v18
	v_mul_f32_e32 v19, v96, v19
	v_mfma_f32_32x32x16_bf16 v[80:95], v[176:179], v[106:109], v[80:95]
	v_mul_f32_e32 v20, v96, v20
	v_mul_f32_e32 v21, v96, v21
	v_mul_f32_e32 v22, v96, v22
	v_mul_f32_e32 v23, v96, v23
	v_mfma_f32_32x32x16_bf16 v[64:79], v[142:145], v[110:113], v[64:79]
	v_mul_f32_e32 v24, v96, v24
	v_mul_f32_e32 v25, v96, v25
	v_mul_f32_e32 v26, v96, v26
	v_mul_f32_e32 v27, v96, v27
	v_mfma_f32_32x32x16_bf16 v[80:95], v[184:187], v[110:113], v[80:95]
	v_mul_f32_e32 v28, v96, v28
	v_mul_f32_e32 v29, v96, v29
	v_mul_f32_e32 v30, v96, v30
	v_mul_f32_e32 v31, v96, v31
	v_add_u32_e32 v110, v171, v169
	v_mfma_f32_32x32x16_bf16 v[64:79], v[146:149], v[114:117], v[64:79]
	v_mul_f32_e32 v32, v96, v32
	v_mul_f32_e32 v33, v96, v33
	v_mul_f32_e32 v34, v96, v34
	v_mul_f32_e32 v35, v96, v35
	v_mfma_f32_32x32x16_bf16 v[80:95], v[196:199], v[114:117], v[80:95]
	v_mul_f32_e32 v36, v96, v36
	v_mul_f32_e32 v37, v96, v37
	v_mul_f32_e32 v38, v96, v38
	v_mul_f32_e32 v39, v96, v39
	v_mfma_f32_32x32x16_bf16 v[64:79], v[150:153], v[118:121], v[64:79]
	v_mul_f32_e32 v40, v96, v40
	v_mul_f32_e32 v41, v96, v41
	v_mul_f32_e32 v42, v96, v42
	v_mul_f32_e32 v43, v96, v43
	v_mfma_f32_32x32x16_bf16 v[80:95], v[200:203], v[118:121], v[80:95]
	v_mul_f32_e32 v44, v96, v44
	v_mul_f32_e32 v45, v96, v45
	v_mul_f32_e32 v46, v96, v46
	v_mul_f32_e32 v47, v96, v47
	v_mfma_f32_32x32x16_bf16 v[64:79], v[154:157], v[122:125], v[64:79]
	v_mul_f32_e32 v48, v96, v48
	v_mul_f32_e32 v49, v96, v49
	v_mul_f32_e32 v50, v96, v50
	v_mul_f32_e32 v51, v96, v51
	v_mfma_f32_32x32x16_bf16 v[80:95], v[204:207], v[122:125], v[80:95]
	v_mul_f32_e32 v52, v96, v52
	v_mul_f32_e32 v53, v96, v53
	v_mul_f32_e32 v54, v96, v54
	v_mul_f32_e32 v55, v96, v55
	v_mfma_f32_32x32x16_bf16 v[64:79], v[158:161], v[126:129], v[64:79]
	v_mul_f32_e32 v56, v96, v56
	v_mul_f32_e32 v57, v96, v57
	v_mul_f32_e32 v58, v96, v58
	v_mul_f32_e32 v59, v96, v59
	v_mfma_f32_32x32x16_bf16 v[80:95], v[208:211], v[126:129], v[80:95]
	v_mul_f32_e32 v60, v96, v60
	v_mul_f32_e32 v61, v96, v61
	v_mul_f32_e32 v62, v96, v62
	v_mul_f32_e32 v63, v96, v63
	ds_read_b128 v[162:165], v110 offset:40960
	ds_read_b128 v[130:133], v110 offset:41984
	ds_read_b128 v[114:117], v110 offset:43008
	ds_read_b128 v[98:101], v110 offset:44032
	ds_read_b128 v[158:161], v110 offset:45056
	ds_read_b128 v[134:137], v110 offset:46080
	ds_read_b128 v[118:121], v110 offset:47104
	ds_read_b128 v[102:105], v110 offset:48128
	ds_read_b128 v[150:153], v110 offset:49152
	ds_read_b128 v[138:141], v110 offset:50176
	ds_read_b128 v[122:125], v110 offset:51200
	ds_read_b128 v[106:109], v110 offset:52224
	ds_read_b128 v[146:149], v110 offset:53248
	ds_read_b128 v[142:145], v110 offset:54272
	ds_read_b128 v[126:129], v110 offset:55296
	ds_read_b128 v[110:113], v110 offset:56320
	v_cvt_pk_bf16_f32 v154, v64, v65
	v_cvt_pk_bf16_f32 v155, v66, v67
	v_cvt_pk_bf16_f32 v156, v68, v69
	v_cvt_pk_bf16_f32 v157, v70, v71
	v_cvt_pk_bf16_f32 v72, v72, v73
	v_cvt_pk_bf16_f32 v73, v74, v75
	v_cvt_pk_bf16_f32 v74, v76, v77
	v_cvt_pk_bf16_f32 v75, v78, v79
	v_cvt_pk_bf16_f32 v68, v80, v81
	v_cvt_pk_bf16_f32 v69, v82, v83
	v_cvt_pk_bf16_f32 v70, v84, v85
	v_cvt_pk_bf16_f32 v71, v86, v87
	v_cvt_pk_bf16_f32 v64, v88, v89
	v_cvt_pk_bf16_f32 v65, v90, v91
	v_cvt_pk_bf16_f32 v66, v92, v93
	v_cvt_pk_bf16_f32 v67, v94, v95
	ds_write_b128 v167, v[154:157]
	ds_write_b128 v167, v[72:75] offset:1024
	ds_write_b128 v167, v[68:71] offset:2048
	ds_write_b128 v167, v[64:67] offset:3072
	s_mov_b64 s[4:5], exec
	s_mov_b64 exec, 1
	v_readlane_b32 s9, v254, 21
	v_mov_b32_e32 v77, s8
	s_nop 0
	v_mov_b32_e32 v76, s9
	ds_write_b32 v76, v77
	s_mov_b64 exec, s[4:5]
	s_branch .LBB0_368
